# scan: LDS operand reads issued as one burst per step (3 register sets, 2 steps ahead) instead of interleaved
# speedup vs baseline: 1.0401x; 1.0401x over previous
; DI void scan_task(const Params& p, int l, int isP, int b, int h, int rg, char* smem, const bool dry) {
;     ...
;     for (int s = 0; s < 32; s++) {
;       f32x4 w4n = w4, a4n = a4, b4n = b4;
;       uint2 urn = ur, ukn = uk;
;       float vn = v;
;       if (s < 31) {
;         w4n = *(const f32x4*)(fw + (s + 1) * 64);
;         a4n = *(const f32x4*)(fa + (s + 1) * 64);
;         b4n = *(const f32x4*)(fb + (s + 1) * 64);
;         urn = *(const uint2*)(pr + (s + 1) * 128);
;         ukn = *(const uint2*)(pk + (s + 1) * 128);
;         vn = vb[(s + 1) * 16];
;       }
;       __builtin_amdgcn_sched_barrier(0);
;       const f32x2 klo = {__uint_as_float(uk.x << 16), __uint_as_float(uk.x & 0xFFFF0000u)};
;       const f32x2 khi = {__uint_as_float(uk.y << 16), __uint_as_float(uk.y & 0xFFFF0000u)};
;       const f32x2 rlo = {__uint_as_float(ur.x << 16), __uint_as_float(ur.x & 0xFFFF0000u)};
;       const f32x2 rhi = {__uint_as_float(ur.y << 16), __uint_as_float(ur.y & 0xFFFF0000u)};
;       const f32x2 vv = {v, v};
;       const f32x2 t = Sa * a4.lo + Sb * a4.hi;
;       const f32x2 na = Sa * w4.lo + vv * klo;
;       const f32x2 nb = Sb * w4.hi + vv * khi;
;       float sa = t.x + t.y;
;       float yp = yprev;
;       rowsum16x2(sa, yp);
;       if (s >= 1 && s <= 16) ykeep0 = (jq == s - 1) ? yp : ykeep0;
;       if (s >= 17) ykeep1 = (jq == s - 17) ? yp : ykeep1;
;       const f32x2 sv = {sa, sa};
;       Sa = na + sv * b4.lo;
;       Sb = nb + sv * b4.hi;
;       const f32x2 yy = Sa * rlo + Sb * rhi;
;       yprev = yy.x + yy.y;
;       w4 = w4n; a4 = a4n; b4 = b4n; ur = urn; uk = ukn; v = vn;
;     }
.Lscan_noldA:
	s_waitcnt lgkmcnt(6)
	ds_read_b128 v[228:231], v76 offset:4608
	ds_read_b128 v[240:243], v76 offset:16896
	ds_read_b128 v[224:227], v76 offset:512
	ds_read_b128 v[232:235], v76 offset:8704
	ds_read_b128 v[236:239], v76 offset:12800
	v_pk_mul_f32 v[56:57], v[4:5], v[12:13]
	v_pk_fma_f32 v[56:57], v[6:7], v[14:15], v[56:57]
	v_add_f32_e32 v58, v56, v57
	v_pk_mul_f32 v[60:61], v[48:49], v[24:25] op_sel_hi:[0,1]
	v_pk_mul_f32 v[62:63], v[48:49], v[26:27] op_sel_hi:[0,1]
	v_add_f32_dpp v58, v58, v58 quad_perm:[1,0,3,2] row_mask:0xf bank_mask:0xf bound_ctrl:1
	v_pk_fma_f32 v[60:61], v[4:5], v[8:9], v[60:61]
	v_pk_fma_f32 v[62:63], v[6:7], v[10:11], v[62:63]
	v_add_f32_dpp v58, v58, v58 quad_perm:[2,3,0,1] row_mask:0xf bank_mask:0xf bound_ctrl:1
	s_nop 1
	v_add_f32_dpp v58, v58, v58 row_half_mirror row_mask:0xf bank_mask:0xf bound_ctrl:1
	s_nop 1
	v_add_f32_dpp v58, v58, v58 row_mirror row_mask:0xf bank_mask:0xf bound_ctrl:1
	v_pk_fma_f32 v[4:5], v[58:59], v[16:17], v[60:61] op_sel_hi:[0,1,1]
	v_pk_fma_f32 v[6:7], v[58:59], v[18:19], v[62:63] op_sel_hi:[0,1,1]
	s_waitcnt lgkmcnt(6)
	ds_read_b128 v[12:15], v76 offset:4864
	ds_read_b128 v[24:27], v76 offset:17152
	ds_read_b128 v[8:11], v76 offset:768
	ds_read_b128 v[16:19], v76 offset:8960
	ds_read_b128 v[52:55], v77 offset:20496
	v_pk_mul_f32 v[56:57], v[4:5], v[32:33]
	v_pk_mul_f32 v[64:65], v[4:5], v[20:21]
	v_pk_fma_f32 v[56:57], v[6:7], v[34:35], v[56:57]
	v_pk_fma_f32 v[64:65], v[6:7], v[22:23], v[64:65]
	v_add_f32_e32 v58, v56, v57
	v_pk_mul_f32 v[60:61], v[48:49], v[44:45] op_sel:[1,0] op_sel_hi:[1,1]
	v_pk_mul_f32 v[62:63], v[48:49], v[46:47] op_sel:[1,0] op_sel_hi:[1,1]
	v_add_f32_dpp v58, v58, v58 quad_perm:[1,0,3,2] row_mask:0xf bank_mask:0xf bound_ctrl:1
	v_pk_fma_f32 v[60:61], v[4:5], v[28:29], v[60:61]
	v_add_f32_e32 v66, v64, v65
	v_add_f32_dpp v58, v58, v58 quad_perm:[2,3,0,1] row_mask:0xf bank_mask:0xf bound_ctrl:1
	v_pk_fma_f32 v[62:63], v[6:7], v[30:31], v[62:63]
	s_nop 0
	v_add_f32_dpp v58, v58, v58 row_half_mirror row_mask:0xf bank_mask:0xf bound_ctrl:1
	ds_read_b128 v[20:23], v76 offset:13056
	s_nop 0
	v_add_f32_dpp v58, v58, v58 row_mirror row_mask:0xf bank_mask:0xf bound_ctrl:1
	v_pk_fma_f32 v[4:5], v[58:59], v[36:37], v[60:61] op_sel_hi:[0,1,1]
	v_pk_fma_f32 v[6:7], v[58:59], v[38:39], v[62:63] op_sel_hi:[0,1,1]
	s_waitcnt lgkmcnt(7)
	ds_read_b128 v[32:35], v76 offset:5120
	ds_read_b128 v[44:47], v76 offset:17408
	ds_read_b128 v[28:31], v76 offset:1024
	ds_read_b128 v[36:39], v76 offset:9216
	v_pk_mul_f32 v[56:57], v[4:5], v[228:229]
	v_pk_mul_f32 v[64:65], v[4:5], v[40:41]
	v_pk_fma_f32 v[56:57], v[6:7], v[230:231], v[56:57]
	v_pk_fma_f32 v[64:65], v[6:7], v[42:43], v[64:65]
	v_add_f32_e32 v58, v56, v57
	v_pk_mul_f32 v[60:61], v[50:51], v[240:241] op_sel_hi:[0,1]
	v_pk_mul_f32 v[62:63], v[50:51], v[242:243] op_sel_hi:[0,1]
	v_add_f32_dpp v58, v58, v58 quad_perm:[1,0,3,2] row_mask:0xf bank_mask:0xf bound_ctrl:1
	v_pk_fma_f32 v[60:61], v[4:5], v[224:225], v[60:61]
	v_add_f32_e32 v67, v64, v65
	v_add_f32_dpp v58, v58, v58 quad_perm:[2,3,0,1] row_mask:0xf bank_mask:0xf bound_ctrl:1
	v_pk_fma_f32 v[62:63], v[6:7], v[226:227], v[62:63]
	v_add_f32_dpp v68, v66, v66 row_mirror row_mask:0xf bank_mask:0x3
	v_add_f32_dpp v58, v58, v58 row_half_mirror row_mask:0xf bank_mask:0xf bound_ctrl:1
	s_nop 0
	v_add_f32_dpp v68, v67, v67 row_mirror row_mask:0xf bank_mask:0xc
	ds_read_b128 v[40:43], v76 offset:13312
	v_add_f32_dpp v58, v58, v58 row_mirror row_mask:0xf bank_mask:0xf bound_ctrl:1
	v_pk_fma_f32 v[4:5], v[58:59], v[232:233], v[60:61] op_sel_hi:[0,1,1]
	v_pk_fma_f32 v[6:7], v[58:59], v[234:235], v[62:63] op_sel_hi:[0,1,1]
	s_waitcnt lgkmcnt(7)
	ds_read_b128 v[228:231], v76 offset:5376
	ds_read_b128 v[240:243], v76 offset:17664
	ds_read_b128 v[224:227], v76 offset:1280
	ds_read_b128 v[232:235], v76 offset:9472
	v_pk_mul_f32 v[56:57], v[4:5], v[12:13]
	v_pk_mul_f32 v[64:65], v[4:5], v[236:237]
	v_pk_fma_f32 v[56:57], v[6:7], v[14:15], v[56:57]
	v_pk_fma_f32 v[64:65], v[6:7], v[238:239], v[64:65]
	v_add_f32_e32 v58, v56, v57
	v_pk_mul_f32 v[60:61], v[50:51], v[24:25] op_sel:[1,0] op_sel_hi:[1,1]
	v_pk_mul_f32 v[62:63], v[50:51], v[26:27] op_sel:[1,0] op_sel_hi:[1,1]
	v_add_f32_dpp v58, v58, v58 quad_perm:[1,0,3,2] row_mask:0xf bank_mask:0xf bound_ctrl:1
	v_pk_fma_f32 v[60:61], v[4:5], v[8:9], v[60:61]
	v_add_f32_e32 v66, v64, v65
	v_add_f32_dpp v58, v58, v58 quad_perm:[2,3,0,1] row_mask:0xf bank_mask:0xf bound_ctrl:1
	v_pk_fma_f32 v[62:63], v[6:7], v[10:11], v[62:63]
	s_nop 0
	v_add_f32_dpp v58, v58, v58 row_half_mirror row_mask:0xf bank_mask:0xf bound_ctrl:1
	ds_read_b128 v[236:239], v76 offset:13568
	s_nop 0
	v_add_f32_dpp v58, v58, v58 row_mirror row_mask:0xf bank_mask:0xf bound_ctrl:1
	v_pk_fma_f32 v[4:5], v[58:59], v[16:17], v[60:61] op_sel_hi:[0,1,1]
	v_pk_fma_f32 v[6:7], v[58:59], v[18:19], v[62:63] op_sel_hi:[0,1,1]
	s_waitcnt lgkmcnt(6)
	ds_read_b128 v[12:15], v76 offset:5632
	ds_read_b128 v[24:27], v76 offset:17920
	ds_read_b128 v[8:11], v76 offset:1536
	ds_read_b128 v[16:19], v76 offset:9728
	v_pk_mul_f32 v[56:57], v[4:5], v[32:33]
	v_pk_mul_f32 v[64:65], v[4:5], v[20:21]
	v_pk_fma_f32 v[56:57], v[6:7], v[34:35], v[56:57]
	v_pk_fma_f32 v[64:65], v[6:7], v[22:23], v[64:65]
	v_add_f32_e32 v58, v56, v57
	v_pk_mul_f32 v[60:61], v[52:53], v[44:45] op_sel_hi:[0,1]
	v_pk_mul_f32 v[62:63], v[52:53], v[46:47] op_sel_hi:[0,1]
	v_add_f32_dpp v58, v58, v58 quad_perm:[1,0,3,2] row_mask:0xf bank_mask:0xf bound_ctrl:1
	v_pk_fma_f32 v[60:61], v[4:5], v[28:29], v[60:61]
	v_add_f32_e32 v67, v64, v65
	v_add_f32_dpp v58, v58, v58 quad_perm:[2,3,0,1] row_mask:0xf bank_mask:0xf bound_ctrl:1
	v_pk_fma_f32 v[62:63], v[6:7], v[30:31], v[62:63]
	v_add_f32_dpp v69, v66, v66 row_mirror row_mask:0xf bank_mask:0x3
	v_add_f32_dpp v58, v58, v58 row_half_mirror row_mask:0xf bank_mask:0xf bound_ctrl:1
	s_nop 0
	v_add_f32_dpp v69, v67, v67 row_mirror row_mask:0xf bank_mask:0xc
	ds_read_b128 v[20:23], v76 offset:13824
	v_add_f32_dpp v58, v58, v58 row_mirror row_mask:0xf bank_mask:0xf bound_ctrl:1
	v_pk_fma_f32 v[4:5], v[58:59], v[36:37], v[60:61] op_sel_hi:[0,1,1]
	v_pk_fma_f32 v[6:7], v[58:59], v[38:39], v[62:63] op_sel_hi:[0,1,1]
	s_waitcnt lgkmcnt(6)
; DI void scan_task(const Params& p, int l, int isP, int b, int h, int rg, char* smem, const bool dry) {
;     ...
;     for (int s = 0; s < 32; s++) {
;       f32x4 w4n = w4, a4n = a4, b4n = b4;
;       uint2 urn = ur, ukn = uk;
;       float vn = v;
;       if (s < 31) {
;         w4n = *(const f32x4*)(fw + (s + 1) * 64);
;         a4n = *(const f32x4*)(fa + (s + 1) * 64);
;         b4n = *(const f32x4*)(fb + (s + 1) * 64);
;         urn = *(const uint2*)(pr + (s + 1) * 128);
;         ukn = *(const uint2*)(pk + (s + 1) * 128);
;         vn = vb[(s + 1) * 16];
;       }
;       __builtin_amdgcn_sched_barrier(0);
;       const f32x2 klo = {__uint_as_float(uk.x << 16), __uint_as_float(uk.x & 0xFFFF0000u)};
;       const f32x2 khi = {__uint_as_float(uk.y << 16), __uint_as_float(uk.y & 0xFFFF0000u)};
;       const f32x2 rlo = {__uint_as_float(ur.x << 16), __uint_as_float(ur.x & 0xFFFF0000u)};
;       const f32x2 rhi = {__uint_as_float(ur.y << 16), __uint_as_float(ur.y & 0xFFFF0000u)};
;       const f32x2 vv = {v, v};
;       const f32x2 t = Sa * a4.lo + Sb * a4.hi;
;       const f32x2 na = Sa * w4.lo + vv * klo;
;       const f32x2 nb = Sb * w4.hi + vv * khi;
;       float sa = t.x + t.y;
;       float yp = yprev;
;       rowsum16x2(sa, yp);
;       if (s >= 1 && s <= 16) ykeep0 = (jq == s - 1) ? yp : ykeep0;
;       if (s >= 17) ykeep1 = (jq == s - 17) ? yp : ykeep1;
;       const f32x2 sv = {sa, sa};
;       Sa = na + sv * b4.lo;
;       Sb = nb + sv * b4.hi;
;       const f32x2 yy = Sa * rlo + Sb * rhi;
;       yprev = yy.x + yy.y;
;       w4 = w4n; a4 = a4n; b4 = b4n; ur = urn; uk = ukn; v = vn;
;     }
	ds_read_b128 v[32:35], v76 offset:5888
	ds_read_b128 v[44:47], v76 offset:18176
	ds_read_b128 v[28:31], v76 offset:1792
	ds_read_b128 v[36:39], v76 offset:9984
	ds_read_b128 v[48:51], v77 offset:20512
	v_pk_mul_f32 v[56:57], v[4:5], v[228:229]
	v_pk_mul_f32 v[64:65], v[4:5], v[40:41]
	v_pk_fma_f32 v[56:57], v[6:7], v[230:231], v[56:57]
	v_pk_fma_f32 v[64:65], v[6:7], v[42:43], v[64:65]
	v_add_f32_e32 v58, v56, v57
	v_pk_mul_f32 v[60:61], v[52:53], v[240:241] op_sel:[1,0] op_sel_hi:[1,1]
	v_pk_mul_f32 v[62:63], v[52:53], v[242:243] op_sel:[1,0] op_sel_hi:[1,1]
	v_add_f32_dpp v58, v58, v58 quad_perm:[1,0,3,2] row_mask:0xf bank_mask:0xf bound_ctrl:1
	v_pk_fma_f32 v[60:61], v[4:5], v[224:225], v[60:61]
	v_add_f32_e32 v66, v64, v65
	v_add_f32_dpp v58, v58, v58 quad_perm:[2,3,0,1] row_mask:0xf bank_mask:0xf bound_ctrl:1
	v_pk_fma_f32 v[62:63], v[6:7], v[226:227], v[62:63]
	v_add_f32_dpp v68, v68, v68 row_half_mirror row_mask:0xf bank_mask:0x5
	v_add_f32_dpp v58, v58, v58 row_half_mirror row_mask:0xf bank_mask:0xf bound_ctrl:1
	s_nop 0
	v_add_f32_dpp v68, v69, v69 row_half_mirror row_mask:0xf bank_mask:0xa
	ds_read_b128 v[40:43], v76 offset:14080
	v_add_f32_dpp v58, v58, v58 row_mirror row_mask:0xf bank_mask:0xf bound_ctrl:1
	v_pk_fma_f32 v[4:5], v[58:59], v[232:233], v[60:61] op_sel_hi:[0,1,1]
	v_pk_fma_f32 v[6:7], v[58:59], v[234:235], v[62:63] op_sel_hi:[0,1,1]
	s_waitcnt lgkmcnt(7)
	ds_read_b128 v[228:231], v76 offset:6144
	ds_read_b128 v[240:243], v76 offset:18432
	ds_read_b128 v[224:227], v76 offset:2048
	ds_read_b128 v[232:235], v76 offset:10240
	v_pk_mul_f32 v[56:57], v[4:5], v[12:13]
	v_pk_mul_f32 v[64:65], v[4:5], v[236:237]
	v_pk_fma_f32 v[56:57], v[6:7], v[14:15], v[56:57]
	v_pk_fma_f32 v[64:65], v[6:7], v[238:239], v[64:65]
	v_add_f32_e32 v58, v56, v57
	v_pk_mul_f32 v[60:61], v[54:55], v[24:25] op_sel_hi:[0,1]
	v_pk_mul_f32 v[62:63], v[54:55], v[26:27] op_sel_hi:[0,1]
	v_add_f32_dpp v58, v58, v58 quad_perm:[1,0,3,2] row_mask:0xf bank_mask:0xf bound_ctrl:1
	v_pk_fma_f32 v[60:61], v[4:5], v[8:9], v[60:61]
	v_add_f32_e32 v67, v64, v65
	v_add_f32_dpp v58, v58, v58 quad_perm:[2,3,0,1] row_mask:0xf bank_mask:0xf bound_ctrl:1
	v_pk_fma_f32 v[62:63], v[6:7], v[10:11], v[62:63]
	v_add_f32_dpp v70, v66, v66 row_mirror row_mask:0xf bank_mask:0x3
	v_add_f32_dpp v58, v58, v58 row_half_mirror row_mask:0xf bank_mask:0xf bound_ctrl:1
	s_nop 0
	v_add_f32_dpp v70, v67, v67 row_mirror row_mask:0xf bank_mask:0xc
	ds_read_b128 v[236:239], v76 offset:14336
	v_add_f32_dpp v58, v58, v58 row_mirror row_mask:0xf bank_mask:0xf bound_ctrl:1
	v_pk_fma_f32 v[4:5], v[58:59], v[16:17], v[60:61] op_sel_hi:[0,1,1]
	v_pk_fma_f32 v[6:7], v[58:59], v[18:19], v[62:63] op_sel_hi:[0,1,1]
	s_waitcnt lgkmcnt(7)
	ds_read_b128 v[12:15], v76 offset:6400
	ds_read_b128 v[24:27], v76 offset:18688
	ds_read_b128 v[8:11], v76 offset:2304
	ds_read_b128 v[16:19], v76 offset:10496
	v_pk_mul_f32 v[56:57], v[4:5], v[32:33]
	v_pk_mul_f32 v[64:65], v[4:5], v[20:21]
	v_pk_fma_f32 v[56:57], v[6:7], v[34:35], v[56:57]
	v_pk_fma_f32 v[64:65], v[6:7], v[22:23], v[64:65]
	v_add_f32_e32 v58, v56, v57
	v_pk_mul_f32 v[60:61], v[54:55], v[44:45] op_sel:[1,0] op_sel_hi:[1,1]
	v_pk_mul_f32 v[62:63], v[54:55], v[46:47] op_sel:[1,0] op_sel_hi:[1,1]
	v_add_f32_dpp v58, v58, v58 quad_perm:[1,0,3,2] row_mask:0xf bank_mask:0xf bound_ctrl:1
	v_pk_fma_f32 v[60:61], v[4:5], v[28:29], v[60:61]
	v_add_f32_e32 v66, v64, v65
	v_add_f32_dpp v58, v58, v58 quad_perm:[2,3,0,1] row_mask:0xf bank_mask:0xf bound_ctrl:1
	v_pk_fma_f32 v[62:63], v[6:7], v[30:31], v[62:63]
	s_nop 0
	v_add_f32_dpp v58, v58, v58 row_half_mirror row_mask:0xf bank_mask:0xf bound_ctrl:1
	ds_read_b128 v[20:23], v76 offset:14592
	s_nop 0
	v_add_f32_dpp v58, v58, v58 row_mirror row_mask:0xf bank_mask:0xf bound_ctrl:1
	v_pk_fma_f32 v[4:5], v[58:59], v[36:37], v[60:61] op_sel_hi:[0,1,1]
	v_pk_fma_f32 v[6:7], v[58:59], v[38:39], v[62:63] op_sel_hi:[0,1,1]
	s_waitcnt lgkmcnt(6)
	ds_read_b128 v[32:35], v76 offset:6656
	ds_read_b128 v[44:47], v76 offset:18944
	ds_read_b128 v[28:31], v76 offset:2560
	ds_read_b128 v[36:39], v76 offset:10752
	v_pk_mul_f32 v[56:57], v[4:5], v[228:229]
	v_pk_mul_f32 v[64:65], v[4:5], v[40:41]
	v_pk_fma_f32 v[56:57], v[6:7], v[230:231], v[56:57]
	v_pk_fma_f32 v[64:65], v[6:7], v[42:43], v[64:65]
	v_add_f32_e32 v58, v56, v57
	v_pk_mul_f32 v[60:61], v[48:49], v[240:241] op_sel_hi:[0,1]
	v_pk_mul_f32 v[62:63], v[48:49], v[242:243] op_sel_hi:[0,1]
	v_add_f32_dpp v58, v58, v58 quad_perm:[1,0,3,2] row_mask:0xf bank_mask:0xf bound_ctrl:1
	v_pk_fma_f32 v[60:61], v[4:5], v[224:225], v[60:61]
	v_add_f32_e32 v67, v64, v65
	v_add_f32_dpp v58, v58, v58 quad_perm:[2,3,0,1] row_mask:0xf bank_mask:0xf bound_ctrl:1
	v_pk_fma_f32 v[62:63], v[6:7], v[226:227], v[62:63]
	v_add_f32_dpp v71, v66, v66 row_mirror row_mask:0xf bank_mask:0x3
	v_add_f32_dpp v58, v58, v58 row_half_mirror row_mask:0xf bank_mask:0xf bound_ctrl:1
	s_nop 0
	v_add_f32_dpp v71, v67, v67 row_mirror row_mask:0xf bank_mask:0xc
	ds_read_b128 v[40:43], v76 offset:14848
	v_add_f32_dpp v58, v58, v58 row_mirror row_mask:0xf bank_mask:0xf bound_ctrl:1
	v_pk_fma_f32 v[4:5], v[58:59], v[232:233], v[60:61] op_sel_hi:[0,1,1]
	v_pk_fma_f32 v[6:7], v[58:59], v[234:235], v[62:63] op_sel_hi:[0,1,1]
	s_waitcnt lgkmcnt(6)
; DI void scan_task(const Params& p, int l, int isP, int b, int h, int rg, char* smem, const bool dry) {
;     ...
;     for (int s = 0; s < 32; s++) {
;       f32x4 w4n = w4, a4n = a4, b4n = b4;
;       uint2 urn = ur, ukn = uk;
;       float vn = v;
;       if (s < 31) {
;         w4n = *(const f32x4*)(fw + (s + 1) * 64);
;         a4n = *(const f32x4*)(fa + (s + 1) * 64);
;         b4n = *(const f32x4*)(fb + (s + 1) * 64);
;         urn = *(const uint2*)(pr + (s + 1) * 128);
;         ukn = *(const uint2*)(pk + (s + 1) * 128);
;         vn = vb[(s + 1) * 16];
;       }
;       __builtin_amdgcn_sched_barrier(0);
;       const f32x2 klo = {__uint_as_float(uk.x << 16), __uint_as_float(uk.x & 0xFFFF0000u)};
;       const f32x2 khi = {__uint_as_float(uk.y << 16), __uint_as_float(uk.y & 0xFFFF0000u)};
;       const f32x2 rlo = {__uint_as_float(ur.x << 16), __uint_as_float(ur.x & 0xFFFF0000u)};
;       const f32x2 rhi = {__uint_as_float(ur.y << 16), __uint_as_float(ur.y & 0xFFFF0000u)};
;       const f32x2 vv = {v, v};
;       const f32x2 t = Sa * a4.lo + Sb * a4.hi;
;       const f32x2 na = Sa * w4.lo + vv * klo;
;       const f32x2 nb = Sb * w4.hi + vv * khi;
;       float sa = t.x + t.y;
;       float yp = yprev;
;       rowsum16x2(sa, yp);
;       if (s >= 1 && s <= 16) ykeep0 = (jq == s - 1) ? yp : ykeep0;
;       if (s >= 17) ykeep1 = (jq == s - 17) ? yp : ykeep1;
;       const f32x2 sv = {sa, sa};
;       Sa = na + sv * b4.lo;
;       Sb = nb + sv * b4.hi;
;       const f32x2 yy = Sa * rlo + Sb * rhi;
;       yprev = yy.x + yy.y;
;       w4 = w4n; a4 = a4n; b4 = b4n; ur = urn; uk = ukn; v = vn;
;     }
	ds_read_b128 v[228:231], v76 offset:6912
	ds_read_b128 v[240:243], v76 offset:19200
	ds_read_b128 v[224:227], v76 offset:2816
	ds_read_b128 v[232:235], v76 offset:11008
	ds_read_b128 v[52:55], v77 offset:20528
	v_pk_mul_f32 v[56:57], v[4:5], v[12:13]
	v_pk_mul_f32 v[64:65], v[4:5], v[236:237]
	v_pk_fma_f32 v[56:57], v[6:7], v[14:15], v[56:57]
	v_pk_fma_f32 v[64:65], v[6:7], v[238:239], v[64:65]
	v_add_f32_e32 v58, v56, v57
	v_pk_mul_f32 v[60:61], v[48:49], v[24:25] op_sel:[1,0] op_sel_hi:[1,1]
	v_pk_mul_f32 v[62:63], v[48:49], v[26:27] op_sel:[1,0] op_sel_hi:[1,1]
	v_add_f32_dpp v58, v58, v58 quad_perm:[1,0,3,2] row_mask:0xf bank_mask:0xf bound_ctrl:1
	v_pk_fma_f32 v[60:61], v[4:5], v[8:9], v[60:61]
	v_add_f32_e32 v66, v64, v65
	v_add_f32_dpp v58, v58, v58 quad_perm:[2,3,0,1] row_mask:0xf bank_mask:0xf bound_ctrl:1
	v_pk_fma_f32 v[62:63], v[6:7], v[10:11], v[62:63]
	v_add_f32_dpp v70, v70, v70 row_half_mirror row_mask:0xf bank_mask:0x5
	v_add_f32_dpp v58, v58, v58 row_half_mirror row_mask:0xf bank_mask:0xf bound_ctrl:1
	s_nop 0
	v_add_f32_dpp v70, v71, v71 row_half_mirror row_mask:0xf bank_mask:0xa
	ds_read_b128 v[236:239], v76 offset:15104
	v_add_f32_dpp v58, v58, v58 row_mirror row_mask:0xf bank_mask:0xf bound_ctrl:1
	v_pk_fma_f32 v[4:5], v[58:59], v[16:17], v[60:61] op_sel_hi:[0,1,1]
	v_pk_fma_f32 v[6:7], v[58:59], v[18:19], v[62:63] op_sel_hi:[0,1,1]
	s_waitcnt lgkmcnt(7)
	ds_read_b128 v[12:15], v76 offset:7168
	ds_read_b128 v[24:27], v76 offset:19456
	ds_read_b128 v[8:11], v76 offset:3072
	ds_read_b128 v[16:19], v76 offset:11264
	v_pk_mul_f32 v[56:57], v[4:5], v[32:33]
	v_pk_mul_f32 v[64:65], v[4:5], v[20:21]
	v_pk_fma_f32 v[56:57], v[6:7], v[34:35], v[56:57]
	v_pk_fma_f32 v[64:65], v[6:7], v[22:23], v[64:65]
	v_add_f32_e32 v58, v56, v57
	v_pk_mul_f32 v[60:61], v[50:51], v[44:45] op_sel_hi:[0,1]
	v_pk_mul_f32 v[62:63], v[50:51], v[46:47] op_sel_hi:[0,1]
	v_add_f32_dpp v58, v58, v58 quad_perm:[1,0,3,2] row_mask:0xf bank_mask:0xf bound_ctrl:1
	v_pk_fma_f32 v[60:61], v[4:5], v[28:29], v[60:61]
	v_add_f32_e32 v67, v64, v65
	v_add_f32_dpp v58, v58, v58 quad_perm:[2,3,0,1] row_mask:0xf bank_mask:0xf bound_ctrl:1
	v_pk_fma_f32 v[62:63], v[6:7], v[30:31], v[62:63]
	v_add_f32_dpp v72, v66, v66 row_mirror row_mask:0xf bank_mask:0x3
	v_add_f32_dpp v58, v58, v58 row_half_mirror row_mask:0xf bank_mask:0xf bound_ctrl:1
	s_nop 0
	v_add_f32_dpp v72, v67, v67 row_mirror row_mask:0xf bank_mask:0xc
	ds_read_b128 v[20:23], v76 offset:15360
	v_add_f32_dpp v58, v58, v58 row_mirror row_mask:0xf bank_mask:0xf bound_ctrl:1
	v_pk_fma_f32 v[4:5], v[58:59], v[36:37], v[60:61] op_sel_hi:[0,1,1]
	v_pk_fma_f32 v[6:7], v[58:59], v[38:39], v[62:63] op_sel_hi:[0,1,1]
	s_waitcnt lgkmcnt(7)
	ds_read_b128 v[32:35], v76 offset:7424
	ds_read_b128 v[44:47], v76 offset:19712
	ds_read_b128 v[28:31], v76 offset:3328
	ds_read_b128 v[36:39], v76 offset:11520
	v_pk_mul_f32 v[56:57], v[4:5], v[228:229]
	v_pk_mul_f32 v[64:65], v[4:5], v[40:41]
	v_pk_fma_f32 v[56:57], v[6:7], v[230:231], v[56:57]
	v_pk_fma_f32 v[64:65], v[6:7], v[42:43], v[64:65]
	v_add_f32_e32 v58, v56, v57
	v_pk_mul_f32 v[60:61], v[50:51], v[240:241] op_sel:[1,0] op_sel_hi:[1,1]
	v_pk_mul_f32 v[62:63], v[50:51], v[242:243] op_sel:[1,0] op_sel_hi:[1,1]
	v_add_f32_dpp v58, v58, v58 quad_perm:[1,0,3,2] row_mask:0xf bank_mask:0xf bound_ctrl:1
	v_pk_fma_f32 v[60:61], v[4:5], v[224:225], v[60:61]
	v_add_f32_e32 v66, v64, v65
	v_add_f32_dpp v58, v58, v58 quad_perm:[2,3,0,1] row_mask:0xf bank_mask:0xf bound_ctrl:1
	v_pk_fma_f32 v[62:63], v[6:7], v[226:227], v[62:63]
	s_nop 0
	v_add_f32_dpp v58, v58, v58 row_half_mirror row_mask:0xf bank_mask:0xf bound_ctrl:1
	ds_read_b128 v[40:43], v76 offset:15616
	s_nop 0
	v_add_f32_dpp v58, v58, v58 row_mirror row_mask:0xf bank_mask:0xf bound_ctrl:1
	v_pk_fma_f32 v[4:5], v[58:59], v[232:233], v[60:61] op_sel_hi:[0,1,1]
	v_pk_fma_f32 v[6:7], v[58:59], v[234:235], v[62:63] op_sel_hi:[0,1,1]
	s_waitcnt lgkmcnt(6)
; DI void scan_task(const Params& p, int l, int isP, int b, int h, int rg, char* smem, const bool dry) {
;     ...
;     for (int s = 0; s < 32; s++) {
;       f32x4 w4n = w4, a4n = a4, b4n = b4;
;       uint2 urn = ur, ukn = uk;
;       float vn = v;
;       if (s < 31) {
;         w4n = *(const f32x4*)(fw + (s + 1) * 64);
;         a4n = *(const f32x4*)(fa + (s + 1) * 64);
;         b4n = *(const f32x4*)(fb + (s + 1) * 64);
;         urn = *(const uint2*)(pr + (s + 1) * 128);
;         ukn = *(const uint2*)(pk + (s + 1) * 128);
;         vn = vb[(s + 1) * 16];
;       }
;       __builtin_amdgcn_sched_barrier(0);
;       const f32x2 klo = {__uint_as_float(uk.x << 16), __uint_as_float(uk.x & 0xFFFF0000u)};
;       const f32x2 khi = {__uint_as_float(uk.y << 16), __uint_as_float(uk.y & 0xFFFF0000u)};
;       const f32x2 rlo = {__uint_as_float(ur.x << 16), __uint_as_float(ur.x & 0xFFFF0000u)};
;       const f32x2 rhi = {__uint_as_float(ur.y << 16), __uint_as_float(ur.y & 0xFFFF0000u)};
;       const f32x2 vv = {v, v};
;       const f32x2 t = Sa * a4.lo + Sb * a4.hi;
;       const f32x2 na = Sa * w4.lo + vv * klo;
;       const f32x2 nb = Sb * w4.hi + vv * khi;
;       float sa = t.x + t.y;
;       float yp = yprev;
;       rowsum16x2(sa, yp);
;       if (s >= 1 && s <= 16) ykeep0 = (jq == s - 1) ? yp : ykeep0;
;       if (s >= 17) ykeep1 = (jq == s - 17) ? yp : ykeep1;
;       const f32x2 sv = {sa, sa};
;       Sa = na + sv * b4.lo;
;       Sb = nb + sv * b4.hi;
;       const f32x2 yy = Sa * rlo + Sb * rhi;
;       yprev = yy.x + yy.y;
;       w4 = w4n; a4 = a4n; b4 = b4n; ur = urn; uk = ukn; v = vn;
;     }
;     {
;       const float yl = rowsum16(yprev);
;       ykeep1 = (jq == 15) ? yl : ykeep1;
;     }
;     if (!dry) { yo[0] = ykeep0; yo[(size_t)16 * 512] = ykeep1; }
;     if (more) sstore((c + 1) & 1);
;     __syncthreads();
	ds_read_b128 v[228:231], v76 offset:7680
	ds_read_b128 v[240:243], v76 offset:19968
	ds_read_b128 v[224:227], v76 offset:3584
	ds_read_b128 v[232:235], v76 offset:11776
	v_pk_mul_f32 v[56:57], v[4:5], v[12:13]
	v_pk_mul_f32 v[64:65], v[4:5], v[236:237]
	v_pk_fma_f32 v[56:57], v[6:7], v[14:15], v[56:57]
	v_pk_fma_f32 v[64:65], v[6:7], v[238:239], v[64:65]
	v_add_f32_e32 v58, v56, v57
	v_pk_mul_f32 v[60:61], v[52:53], v[24:25] op_sel_hi:[0,1]
	v_pk_mul_f32 v[62:63], v[52:53], v[26:27] op_sel_hi:[0,1]
	v_add_f32_dpp v58, v58, v58 quad_perm:[1,0,3,2] row_mask:0xf bank_mask:0xf bound_ctrl:1
	v_pk_fma_f32 v[60:61], v[4:5], v[8:9], v[60:61]
	v_add_f32_e32 v67, v64, v65
	v_add_f32_dpp v58, v58, v58 quad_perm:[2,3,0,1] row_mask:0xf bank_mask:0xf bound_ctrl:1
	v_pk_fma_f32 v[62:63], v[6:7], v[10:11], v[62:63]
	v_add_f32_dpp v73, v66, v66 row_mirror row_mask:0xf bank_mask:0x3
	v_add_f32_dpp v58, v58, v58 row_half_mirror row_mask:0xf bank_mask:0xf bound_ctrl:1
	s_nop 0
	v_add_f32_dpp v73, v67, v67 row_mirror row_mask:0xf bank_mask:0xc
	ds_read_b128 v[236:239], v76 offset:15872
	v_add_f32_dpp v58, v58, v58 row_mirror row_mask:0xf bank_mask:0xf bound_ctrl:1
	v_pk_fma_f32 v[4:5], v[58:59], v[16:17], v[60:61] op_sel_hi:[0,1,1]
	v_pk_fma_f32 v[6:7], v[58:59], v[18:19], v[62:63] op_sel_hi:[0,1,1]
	s_waitcnt lgkmcnt(6)
	ds_read_b128 v[12:15], v76 offset:7936
	ds_read_b128 v[24:27], v76 offset:20224
	ds_read_b128 v[8:11], v76 offset:3840
	ds_read_b128 v[16:19], v76 offset:12032
	v_pk_mul_f32 v[56:57], v[4:5], v[32:33]
	v_pk_mul_f32 v[64:65], v[4:5], v[20:21]
	v_pk_fma_f32 v[56:57], v[6:7], v[34:35], v[56:57]
	v_pk_fma_f32 v[64:65], v[6:7], v[22:23], v[64:65]
	v_add_f32_e32 v58, v56, v57
	v_pk_mul_f32 v[60:61], v[52:53], v[44:45] op_sel:[1,0] op_sel_hi:[1,1]
	v_pk_mul_f32 v[62:63], v[52:53], v[46:47] op_sel:[1,0] op_sel_hi:[1,1]
	v_add_f32_dpp v58, v58, v58 quad_perm:[1,0,3,2] row_mask:0xf bank_mask:0xf bound_ctrl:1
	v_pk_fma_f32 v[60:61], v[4:5], v[28:29], v[60:61]
	v_add_f32_e32 v66, v64, v65
	v_add_f32_dpp v58, v58, v58 quad_perm:[2,3,0,1] row_mask:0xf bank_mask:0xf bound_ctrl:1
	v_pk_fma_f32 v[62:63], v[6:7], v[30:31], v[62:63]
	v_add_f32_dpp v72, v72, v72 row_half_mirror row_mask:0xf bank_mask:0x5
	v_add_f32_dpp v58, v58, v58 row_half_mirror row_mask:0xf bank_mask:0xf bound_ctrl:1
	s_nop 0
	v_add_f32_dpp v72, v73, v73 row_half_mirror row_mask:0xf bank_mask:0xa
	ds_read_b128 v[20:23], v76 offset:16128
	v_add_f32_dpp v58, v58, v58 row_mirror row_mask:0xf bank_mask:0xf bound_ctrl:1
	v_pk_fma_f32 v[4:5], v[58:59], v[36:37], v[60:61] op_sel_hi:[0,1,1]
	v_pk_fma_f32 v[6:7], v[58:59], v[38:39], v[62:63] op_sel_hi:[0,1,1]
	s_waitcnt lgkmcnt(6)
	v_pk_mul_f32 v[56:57], v[4:5], v[228:229]
	v_pk_mul_f32 v[64:65], v[4:5], v[40:41]
	v_pk_fma_f32 v[56:57], v[6:7], v[230:231], v[56:57]
	v_pk_fma_f32 v[64:65], v[6:7], v[42:43], v[64:65]
	v_add_f32_e32 v58, v56, v57
	v_pk_mul_f32 v[60:61], v[54:55], v[240:241] op_sel_hi:[0,1]
	v_pk_mul_f32 v[62:63], v[54:55], v[242:243] op_sel_hi:[0,1]
	v_add_f32_dpp v58, v58, v58 quad_perm:[1,0,3,2] row_mask:0xf bank_mask:0xf bound_ctrl:1
	v_pk_fma_f32 v[60:61], v[4:5], v[224:225], v[60:61]
	v_add_f32_e32 v67, v64, v65
	v_add_f32_dpp v58, v58, v58 quad_perm:[2,3,0,1] row_mask:0xf bank_mask:0xf bound_ctrl:1
	v_pk_fma_f32 v[62:63], v[6:7], v[226:227], v[62:63]
	v_add_f32_dpp v74, v66, v66 row_mirror row_mask:0xf bank_mask:0x3
	v_add_f32_dpp v58, v58, v58 row_half_mirror row_mask:0xf bank_mask:0xf bound_ctrl:1
	s_nop 0
	v_add_f32_dpp v74, v67, v67 row_mirror row_mask:0xf bank_mask:0xc
	v_add_f32_dpp v58, v58, v58 row_mirror row_mask:0xf bank_mask:0xf bound_ctrl:1
	v_pk_fma_f32 v[4:5], v[58:59], v[232:233], v[60:61] op_sel_hi:[0,1,1]
	v_pk_fma_f32 v[6:7], v[58:59], v[234:235], v[62:63] op_sel_hi:[0,1,1]
	s_waitcnt lgkmcnt(1)
	v_pk_mul_f32 v[56:57], v[4:5], v[12:13]
	v_pk_mul_f32 v[64:65], v[4:5], v[236:237]
	v_pk_fma_f32 v[56:57], v[6:7], v[14:15], v[56:57]
	v_pk_fma_f32 v[64:65], v[6:7], v[238:239], v[64:65]
	v_add_f32_e32 v58, v56, v57
	v_pk_mul_f32 v[60:61], v[54:55], v[24:25] op_sel:[1,0] op_sel_hi:[1,1]
	v_pk_mul_f32 v[62:63], v[54:55], v[26:27] op_sel:[1,0] op_sel_hi:[1,1]
	v_add_f32_dpp v58, v58, v58 quad_perm:[1,0,3,2] row_mask:0xf bank_mask:0xf bound_ctrl:1
	v_pk_fma_f32 v[60:61], v[4:5], v[8:9], v[60:61]
	v_add_f32_e32 v66, v64, v65
	v_add_f32_dpp v58, v58, v58 quad_perm:[2,3,0,1] row_mask:0xf bank_mask:0xf bound_ctrl:1
	v_pk_fma_f32 v[62:63], v[6:7], v[10:11], v[62:63]
	s_nop 0
	v_add_f32_dpp v58, v58, v58 row_half_mirror row_mask:0xf bank_mask:0xf bound_ctrl:1
	s_nop 1
	v_add_f32_dpp v58, v58, v58 row_mirror row_mask:0xf bank_mask:0xf bound_ctrl:1
	v_pk_fma_f32 v[4:5], v[58:59], v[16:17], v[60:61] op_sel_hi:[0,1,1]
	v_pk_fma_f32 v[6:7], v[58:59], v[18:19], v[62:63] op_sel_hi:[0,1,1]
	s_waitcnt lgkmcnt(0)
	v_pk_mul_f32 v[64:65], v[4:5], v[20:21]
	v_pk_fma_f32 v[64:65], v[6:7], v[22:23], v[64:65]
	v_add_f32_e32 v67, v64, v65
	s_cmp_lg_u32 s22, 0
	s_cbranch_scc1 .Lscan_w6A
	s_waitcnt vmcnt(0)
	s_branch .Lscan_wdA

; DI void scan_task(const Params& p, int l, int isP, int b, int h, int rg, char* smem, const bool dry) {
;     ...
;     for (int s = 0; s < 32; s++) {
;       f32x4 w4n = w4, a4n = a4, b4n = b4;
;       uint2 urn = ur, ukn = uk;
;       float vn = v;
;       if (s < 31) {
;         w4n = *(const f32x4*)(fw + (s + 1) * 64);
;         a4n = *(const f32x4*)(fa + (s + 1) * 64);
;         b4n = *(const f32x4*)(fb + (s + 1) * 64);
;         urn = *(const uint2*)(pr + (s + 1) * 128);
;         ukn = *(const uint2*)(pk + (s + 1) * 128);
;         vn = vb[(s + 1) * 16];
;       }
;       __builtin_amdgcn_sched_barrier(0);
;       const f32x2 klo = {__uint_as_float(uk.x << 16), __uint_as_float(uk.x & 0xFFFF0000u)};
;       const f32x2 khi = {__uint_as_float(uk.y << 16), __uint_as_float(uk.y & 0xFFFF0000u)};
;       const f32x2 rlo = {__uint_as_float(ur.x << 16), __uint_as_float(ur.x & 0xFFFF0000u)};
;       const f32x2 rhi = {__uint_as_float(ur.y << 16), __uint_as_float(ur.y & 0xFFFF0000u)};
;       const f32x2 vv = {v, v};
;       const f32x2 t = Sa * a4.lo + Sb * a4.hi;
;       const f32x2 na = Sa * w4.lo + vv * klo;
;       const f32x2 nb = Sb * w4.hi + vv * khi;
;       float sa = t.x + t.y;
;       float yp = yprev;
;       rowsum16x2(sa, yp);
;       if (s >= 1 && s <= 16) ykeep0 = (jq == s - 1) ? yp : ykeep0;
;       if (s >= 17) ykeep1 = (jq == s - 17) ? yp : ykeep1;
;       const f32x2 sv = {sa, sa};
;       Sa = na + sv * b4.lo;
;       Sb = nb + sv * b4.hi;
;       const f32x2 yy = Sa * rlo + Sb * rhi;
;       yprev = yy.x + yy.y;
;       w4 = w4n; a4 = a4n; b4 = b4n; ur = urn; uk = ukn; v = vn;
;     }
.Lscan_noldB:
	s_waitcnt lgkmcnt(6)
	ds_read_b128 v[228:231], v76 offset:26112
	ds_read_b128 v[240:243], v76 offset:38400
	ds_read_b128 v[224:227], v76 offset:22016
	ds_read_b128 v[232:235], v76 offset:30208
	ds_read_b128 v[236:239], v76 offset:34304
	v_pk_mul_f32 v[56:57], v[4:5], v[12:13]
	v_pk_fma_f32 v[56:57], v[6:7], v[14:15], v[56:57]
	v_add_f32_e32 v58, v56, v57
	v_pk_mul_f32 v[60:61], v[48:49], v[24:25] op_sel_hi:[0,1]
	v_pk_mul_f32 v[62:63], v[48:49], v[26:27] op_sel_hi:[0,1]
	v_add_f32_dpp v58, v58, v58 quad_perm:[1,0,3,2] row_mask:0xf bank_mask:0xf bound_ctrl:1
	v_pk_fma_f32 v[60:61], v[4:5], v[8:9], v[60:61]
	v_pk_fma_f32 v[62:63], v[6:7], v[10:11], v[62:63]
	v_add_f32_dpp v58, v58, v58 quad_perm:[2,3,0,1] row_mask:0xf bank_mask:0xf bound_ctrl:1
	s_nop 1
	v_add_f32_dpp v58, v58, v58 row_half_mirror row_mask:0xf bank_mask:0xf bound_ctrl:1
	s_nop 1
	v_add_f32_dpp v58, v58, v58 row_mirror row_mask:0xf bank_mask:0xf bound_ctrl:1
	v_pk_fma_f32 v[4:5], v[58:59], v[16:17], v[60:61] op_sel_hi:[0,1,1]
	v_pk_fma_f32 v[6:7], v[58:59], v[18:19], v[62:63] op_sel_hi:[0,1,1]
	s_waitcnt lgkmcnt(6)
	ds_read_b128 v[12:15], v76 offset:26368
	ds_read_b128 v[24:27], v76 offset:38656
	ds_read_b128 v[8:11], v76 offset:22272
	ds_read_b128 v[16:19], v76 offset:30464
	ds_read_b128 v[52:55], v77 offset:42000
	v_pk_mul_f32 v[56:57], v[4:5], v[32:33]
	v_pk_mul_f32 v[64:65], v[4:5], v[20:21]
	v_pk_fma_f32 v[56:57], v[6:7], v[34:35], v[56:57]
	v_pk_fma_f32 v[64:65], v[6:7], v[22:23], v[64:65]
	v_add_f32_e32 v58, v56, v57
	v_pk_mul_f32 v[60:61], v[48:49], v[44:45] op_sel:[1,0] op_sel_hi:[1,1]
	v_pk_mul_f32 v[62:63], v[48:49], v[46:47] op_sel:[1,0] op_sel_hi:[1,1]
	v_add_f32_dpp v58, v58, v58 quad_perm:[1,0,3,2] row_mask:0xf bank_mask:0xf bound_ctrl:1
	v_pk_fma_f32 v[60:61], v[4:5], v[28:29], v[60:61]
	v_add_f32_e32 v66, v64, v65
	v_add_f32_dpp v58, v58, v58 quad_perm:[2,3,0,1] row_mask:0xf bank_mask:0xf bound_ctrl:1
	v_pk_fma_f32 v[62:63], v[6:7], v[30:31], v[62:63]
	s_nop 0
	v_add_f32_dpp v58, v58, v58 row_half_mirror row_mask:0xf bank_mask:0xf bound_ctrl:1
	ds_read_b128 v[20:23], v76 offset:34560
	s_nop 0
	v_add_f32_dpp v58, v58, v58 row_mirror row_mask:0xf bank_mask:0xf bound_ctrl:1
	v_pk_fma_f32 v[4:5], v[58:59], v[36:37], v[60:61] op_sel_hi:[0,1,1]
	v_pk_fma_f32 v[6:7], v[58:59], v[38:39], v[62:63] op_sel_hi:[0,1,1]
	s_waitcnt lgkmcnt(7)
	ds_read_b128 v[32:35], v76 offset:26624
	ds_read_b128 v[44:47], v76 offset:38912
	ds_read_b128 v[28:31], v76 offset:22528
	ds_read_b128 v[36:39], v76 offset:30720
	v_pk_mul_f32 v[56:57], v[4:5], v[228:229]
	v_pk_mul_f32 v[64:65], v[4:5], v[40:41]
	v_pk_fma_f32 v[56:57], v[6:7], v[230:231], v[56:57]
	v_pk_fma_f32 v[64:65], v[6:7], v[42:43], v[64:65]
	v_add_f32_e32 v58, v56, v57
	v_pk_mul_f32 v[60:61], v[50:51], v[240:241] op_sel_hi:[0,1]
	v_pk_mul_f32 v[62:63], v[50:51], v[242:243] op_sel_hi:[0,1]
	v_add_f32_dpp v58, v58, v58 quad_perm:[1,0,3,2] row_mask:0xf bank_mask:0xf bound_ctrl:1
	v_pk_fma_f32 v[60:61], v[4:5], v[224:225], v[60:61]
	v_add_f32_e32 v67, v64, v65
	v_add_f32_dpp v58, v58, v58 quad_perm:[2,3,0,1] row_mask:0xf bank_mask:0xf bound_ctrl:1
	v_pk_fma_f32 v[62:63], v[6:7], v[226:227], v[62:63]
	v_add_f32_dpp v68, v66, v66 row_mirror row_mask:0xf bank_mask:0x3
	v_add_f32_dpp v58, v58, v58 row_half_mirror row_mask:0xf bank_mask:0xf bound_ctrl:1
	s_nop 0
	v_add_f32_dpp v68, v67, v67 row_mirror row_mask:0xf bank_mask:0xc
	ds_read_b128 v[40:43], v76 offset:34816
	v_add_f32_dpp v58, v58, v58 row_mirror row_mask:0xf bank_mask:0xf bound_ctrl:1
	v_pk_fma_f32 v[4:5], v[58:59], v[232:233], v[60:61] op_sel_hi:[0,1,1]
	v_pk_fma_f32 v[6:7], v[58:59], v[234:235], v[62:63] op_sel_hi:[0,1,1]
	s_waitcnt lgkmcnt(7)
	ds_read_b128 v[228:231], v76 offset:26880
	ds_read_b128 v[240:243], v76 offset:39168
	ds_read_b128 v[224:227], v76 offset:22784
	ds_read_b128 v[232:235], v76 offset:30976
	v_pk_mul_f32 v[56:57], v[4:5], v[12:13]
	v_pk_mul_f32 v[64:65], v[4:5], v[236:237]
	v_pk_fma_f32 v[56:57], v[6:7], v[14:15], v[56:57]
	v_pk_fma_f32 v[64:65], v[6:7], v[238:239], v[64:65]
	v_add_f32_e32 v58, v56, v57
	v_pk_mul_f32 v[60:61], v[50:51], v[24:25] op_sel:[1,0] op_sel_hi:[1,1]
	v_pk_mul_f32 v[62:63], v[50:51], v[26:27] op_sel:[1,0] op_sel_hi:[1,1]
	v_add_f32_dpp v58, v58, v58 quad_perm:[1,0,3,2] row_mask:0xf bank_mask:0xf bound_ctrl:1
	v_pk_fma_f32 v[60:61], v[4:5], v[8:9], v[60:61]
	v_add_f32_e32 v66, v64, v65
	v_add_f32_dpp v58, v58, v58 quad_perm:[2,3,0,1] row_mask:0xf bank_mask:0xf bound_ctrl:1
	v_pk_fma_f32 v[62:63], v[6:7], v[10:11], v[62:63]
	s_nop 0
	v_add_f32_dpp v58, v58, v58 row_half_mirror row_mask:0xf bank_mask:0xf bound_ctrl:1
	ds_read_b128 v[236:239], v76 offset:35072
	s_nop 0
	v_add_f32_dpp v58, v58, v58 row_mirror row_mask:0xf bank_mask:0xf bound_ctrl:1
	v_pk_fma_f32 v[4:5], v[58:59], v[16:17], v[60:61] op_sel_hi:[0,1,1]
	v_pk_fma_f32 v[6:7], v[58:59], v[18:19], v[62:63] op_sel_hi:[0,1,1]
	s_waitcnt lgkmcnt(6)
	ds_read_b128 v[12:15], v76 offset:27136
	ds_read_b128 v[24:27], v76 offset:39424
	ds_read_b128 v[8:11], v76 offset:23040
	ds_read_b128 v[16:19], v76 offset:31232
	v_pk_mul_f32 v[56:57], v[4:5], v[32:33]
	v_pk_mul_f32 v[64:65], v[4:5], v[20:21]
	v_pk_fma_f32 v[56:57], v[6:7], v[34:35], v[56:57]
	v_pk_fma_f32 v[64:65], v[6:7], v[22:23], v[64:65]
	v_add_f32_e32 v58, v56, v57
	v_pk_mul_f32 v[60:61], v[52:53], v[44:45] op_sel_hi:[0,1]
	v_pk_mul_f32 v[62:63], v[52:53], v[46:47] op_sel_hi:[0,1]
	v_add_f32_dpp v58, v58, v58 quad_perm:[1,0,3,2] row_mask:0xf bank_mask:0xf bound_ctrl:1
	v_pk_fma_f32 v[60:61], v[4:5], v[28:29], v[60:61]
	v_add_f32_e32 v67, v64, v65
	v_add_f32_dpp v58, v58, v58 quad_perm:[2,3,0,1] row_mask:0xf bank_mask:0xf bound_ctrl:1
	v_pk_fma_f32 v[62:63], v[6:7], v[30:31], v[62:63]
	v_add_f32_dpp v69, v66, v66 row_mirror row_mask:0xf bank_mask:0x3
	v_add_f32_dpp v58, v58, v58 row_half_mirror row_mask:0xf bank_mask:0xf bound_ctrl:1
	s_nop 0
	v_add_f32_dpp v69, v67, v67 row_mirror row_mask:0xf bank_mask:0xc
	ds_read_b128 v[20:23], v76 offset:35328
	v_add_f32_dpp v58, v58, v58 row_mirror row_mask:0xf bank_mask:0xf bound_ctrl:1
	v_pk_fma_f32 v[4:5], v[58:59], v[36:37], v[60:61] op_sel_hi:[0,1,1]
	v_pk_fma_f32 v[6:7], v[58:59], v[38:39], v[62:63] op_sel_hi:[0,1,1]
	s_waitcnt lgkmcnt(6)
; DI void scan_task(const Params& p, int l, int isP, int b, int h, int rg, char* smem, const bool dry) {
;     ...
;     for (int s = 0; s < 32; s++) {
;       f32x4 w4n = w4, a4n = a4, b4n = b4;
;       uint2 urn = ur, ukn = uk;
;       float vn = v;
;       if (s < 31) {
;         w4n = *(const f32x4*)(fw + (s + 1) * 64);
;         a4n = *(const f32x4*)(fa + (s + 1) * 64);
;         b4n = *(const f32x4*)(fb + (s + 1) * 64);
;         urn = *(const uint2*)(pr + (s + 1) * 128);
;         ukn = *(const uint2*)(pk + (s + 1) * 128);
;         vn = vb[(s + 1) * 16];
;       }
;       __builtin_amdgcn_sched_barrier(0);
;       const f32x2 klo = {__uint_as_float(uk.x << 16), __uint_as_float(uk.x & 0xFFFF0000u)};
;       const f32x2 khi = {__uint_as_float(uk.y << 16), __uint_as_float(uk.y & 0xFFFF0000u)};
;       const f32x2 rlo = {__uint_as_float(ur.x << 16), __uint_as_float(ur.x & 0xFFFF0000u)};
;       const f32x2 rhi = {__uint_as_float(ur.y << 16), __uint_as_float(ur.y & 0xFFFF0000u)};
;       const f32x2 vv = {v, v};
;       const f32x2 t = Sa * a4.lo + Sb * a4.hi;
;       const f32x2 na = Sa * w4.lo + vv * klo;
;       const f32x2 nb = Sb * w4.hi + vv * khi;
;       float sa = t.x + t.y;
;       float yp = yprev;
;       rowsum16x2(sa, yp);
;       if (s >= 1 && s <= 16) ykeep0 = (jq == s - 1) ? yp : ykeep0;
;       if (s >= 17) ykeep1 = (jq == s - 17) ? yp : ykeep1;
;       const f32x2 sv = {sa, sa};
;       Sa = na + sv * b4.lo;
;       Sb = nb + sv * b4.hi;
;       const f32x2 yy = Sa * rlo + Sb * rhi;
;       yprev = yy.x + yy.y;
;       w4 = w4n; a4 = a4n; b4 = b4n; ur = urn; uk = ukn; v = vn;
;     }
	ds_read_b128 v[32:35], v76 offset:27392
	ds_read_b128 v[44:47], v76 offset:39680
	ds_read_b128 v[28:31], v76 offset:23296
	ds_read_b128 v[36:39], v76 offset:31488
	ds_read_b128 v[48:51], v77 offset:42016
	v_pk_mul_f32 v[56:57], v[4:5], v[228:229]
	v_pk_mul_f32 v[64:65], v[4:5], v[40:41]
	v_pk_fma_f32 v[56:57], v[6:7], v[230:231], v[56:57]
	v_pk_fma_f32 v[64:65], v[6:7], v[42:43], v[64:65]
	v_add_f32_e32 v58, v56, v57
	v_pk_mul_f32 v[60:61], v[52:53], v[240:241] op_sel:[1,0] op_sel_hi:[1,1]
	v_pk_mul_f32 v[62:63], v[52:53], v[242:243] op_sel:[1,0] op_sel_hi:[1,1]
	v_add_f32_dpp v58, v58, v58 quad_perm:[1,0,3,2] row_mask:0xf bank_mask:0xf bound_ctrl:1
	v_pk_fma_f32 v[60:61], v[4:5], v[224:225], v[60:61]
	v_add_f32_e32 v66, v64, v65
	v_add_f32_dpp v58, v58, v58 quad_perm:[2,3,0,1] row_mask:0xf bank_mask:0xf bound_ctrl:1
	v_pk_fma_f32 v[62:63], v[6:7], v[226:227], v[62:63]
	v_add_f32_dpp v68, v68, v68 row_half_mirror row_mask:0xf bank_mask:0x5
	v_add_f32_dpp v58, v58, v58 row_half_mirror row_mask:0xf bank_mask:0xf bound_ctrl:1
	s_nop 0
	v_add_f32_dpp v68, v69, v69 row_half_mirror row_mask:0xf bank_mask:0xa
	ds_read_b128 v[40:43], v76 offset:35584
	v_add_f32_dpp v58, v58, v58 row_mirror row_mask:0xf bank_mask:0xf bound_ctrl:1
	v_pk_fma_f32 v[4:5], v[58:59], v[232:233], v[60:61] op_sel_hi:[0,1,1]
	v_pk_fma_f32 v[6:7], v[58:59], v[234:235], v[62:63] op_sel_hi:[0,1,1]
	s_waitcnt lgkmcnt(7)
	ds_read_b128 v[228:231], v76 offset:27648
	ds_read_b128 v[240:243], v76 offset:39936
	ds_read_b128 v[224:227], v76 offset:23552
	ds_read_b128 v[232:235], v76 offset:31744
	v_pk_mul_f32 v[56:57], v[4:5], v[12:13]
	v_pk_mul_f32 v[64:65], v[4:5], v[236:237]
	v_pk_fma_f32 v[56:57], v[6:7], v[14:15], v[56:57]
	v_pk_fma_f32 v[64:65], v[6:7], v[238:239], v[64:65]
	v_add_f32_e32 v58, v56, v57
	v_pk_mul_f32 v[60:61], v[54:55], v[24:25] op_sel_hi:[0,1]
	v_pk_mul_f32 v[62:63], v[54:55], v[26:27] op_sel_hi:[0,1]
	v_add_f32_dpp v58, v58, v58 quad_perm:[1,0,3,2] row_mask:0xf bank_mask:0xf bound_ctrl:1
	v_pk_fma_f32 v[60:61], v[4:5], v[8:9], v[60:61]
	v_add_f32_e32 v67, v64, v65
	v_add_f32_dpp v58, v58, v58 quad_perm:[2,3,0,1] row_mask:0xf bank_mask:0xf bound_ctrl:1
	v_pk_fma_f32 v[62:63], v[6:7], v[10:11], v[62:63]
	v_add_f32_dpp v70, v66, v66 row_mirror row_mask:0xf bank_mask:0x3
	v_add_f32_dpp v58, v58, v58 row_half_mirror row_mask:0xf bank_mask:0xf bound_ctrl:1
	s_nop 0
	v_add_f32_dpp v70, v67, v67 row_mirror row_mask:0xf bank_mask:0xc
	ds_read_b128 v[236:239], v76 offset:35840
	v_add_f32_dpp v58, v58, v58 row_mirror row_mask:0xf bank_mask:0xf bound_ctrl:1
	v_pk_fma_f32 v[4:5], v[58:59], v[16:17], v[60:61] op_sel_hi:[0,1,1]
	v_pk_fma_f32 v[6:7], v[58:59], v[18:19], v[62:63] op_sel_hi:[0,1,1]
	s_waitcnt lgkmcnt(7)
	ds_read_b128 v[12:15], v76 offset:27904
	ds_read_b128 v[24:27], v76 offset:40192
	ds_read_b128 v[8:11], v76 offset:23808
	ds_read_b128 v[16:19], v76 offset:32000
	v_pk_mul_f32 v[56:57], v[4:5], v[32:33]
	v_pk_mul_f32 v[64:65], v[4:5], v[20:21]
	v_pk_fma_f32 v[56:57], v[6:7], v[34:35], v[56:57]
	v_pk_fma_f32 v[64:65], v[6:7], v[22:23], v[64:65]
	v_add_f32_e32 v58, v56, v57
	v_pk_mul_f32 v[60:61], v[54:55], v[44:45] op_sel:[1,0] op_sel_hi:[1,1]
	v_pk_mul_f32 v[62:63], v[54:55], v[46:47] op_sel:[1,0] op_sel_hi:[1,1]
	v_add_f32_dpp v58, v58, v58 quad_perm:[1,0,3,2] row_mask:0xf bank_mask:0xf bound_ctrl:1
	v_pk_fma_f32 v[60:61], v[4:5], v[28:29], v[60:61]
	v_add_f32_e32 v66, v64, v65
	v_add_f32_dpp v58, v58, v58 quad_perm:[2,3,0,1] row_mask:0xf bank_mask:0xf bound_ctrl:1
	v_pk_fma_f32 v[62:63], v[6:7], v[30:31], v[62:63]
	s_nop 0
	v_add_f32_dpp v58, v58, v58 row_half_mirror row_mask:0xf bank_mask:0xf bound_ctrl:1
	ds_read_b128 v[20:23], v76 offset:36096
	s_nop 0
	v_add_f32_dpp v58, v58, v58 row_mirror row_mask:0xf bank_mask:0xf bound_ctrl:1
	v_pk_fma_f32 v[4:5], v[58:59], v[36:37], v[60:61] op_sel_hi:[0,1,1]
	v_pk_fma_f32 v[6:7], v[58:59], v[38:39], v[62:63] op_sel_hi:[0,1,1]
	s_waitcnt lgkmcnt(6)
	ds_read_b128 v[32:35], v76 offset:28160
	ds_read_b128 v[44:47], v76 offset:40448
	ds_read_b128 v[28:31], v76 offset:24064
	ds_read_b128 v[36:39], v76 offset:32256
	v_pk_mul_f32 v[56:57], v[4:5], v[228:229]
	v_pk_mul_f32 v[64:65], v[4:5], v[40:41]
	v_pk_fma_f32 v[56:57], v[6:7], v[230:231], v[56:57]
	v_pk_fma_f32 v[64:65], v[6:7], v[42:43], v[64:65]
	v_add_f32_e32 v58, v56, v57
	v_pk_mul_f32 v[60:61], v[48:49], v[240:241] op_sel_hi:[0,1]
	v_pk_mul_f32 v[62:63], v[48:49], v[242:243] op_sel_hi:[0,1]
	v_add_f32_dpp v58, v58, v58 quad_perm:[1,0,3,2] row_mask:0xf bank_mask:0xf bound_ctrl:1
	v_pk_fma_f32 v[60:61], v[4:5], v[224:225], v[60:61]
	v_add_f32_e32 v67, v64, v65
	v_add_f32_dpp v58, v58, v58 quad_perm:[2,3,0,1] row_mask:0xf bank_mask:0xf bound_ctrl:1
	v_pk_fma_f32 v[62:63], v[6:7], v[226:227], v[62:63]
	v_add_f32_dpp v71, v66, v66 row_mirror row_mask:0xf bank_mask:0x3
	v_add_f32_dpp v58, v58, v58 row_half_mirror row_mask:0xf bank_mask:0xf bound_ctrl:1
	s_nop 0
	v_add_f32_dpp v71, v67, v67 row_mirror row_mask:0xf bank_mask:0xc
	ds_read_b128 v[40:43], v76 offset:36352
	v_add_f32_dpp v58, v58, v58 row_mirror row_mask:0xf bank_mask:0xf bound_ctrl:1
	v_pk_fma_f32 v[4:5], v[58:59], v[232:233], v[60:61] op_sel_hi:[0,1,1]
	v_pk_fma_f32 v[6:7], v[58:59], v[234:235], v[62:63] op_sel_hi:[0,1,1]
	s_waitcnt lgkmcnt(6)
; DI void scan_task(const Params& p, int l, int isP, int b, int h, int rg, char* smem, const bool dry) {
;     ...
;     for (int s = 0; s < 32; s++) {
;       f32x4 w4n = w4, a4n = a4, b4n = b4;
;       uint2 urn = ur, ukn = uk;
;       float vn = v;
;       if (s < 31) {
;         w4n = *(const f32x4*)(fw + (s + 1) * 64);
;         a4n = *(const f32x4*)(fa + (s + 1) * 64);
;         b4n = *(const f32x4*)(fb + (s + 1) * 64);
;         urn = *(const uint2*)(pr + (s + 1) * 128);
;         ukn = *(const uint2*)(pk + (s + 1) * 128);
;         vn = vb[(s + 1) * 16];
;       }
;       __builtin_amdgcn_sched_barrier(0);
;       const f32x2 klo = {__uint_as_float(uk.x << 16), __uint_as_float(uk.x & 0xFFFF0000u)};
;       const f32x2 khi = {__uint_as_float(uk.y << 16), __uint_as_float(uk.y & 0xFFFF0000u)};
;       const f32x2 rlo = {__uint_as_float(ur.x << 16), __uint_as_float(ur.x & 0xFFFF0000u)};
;       const f32x2 rhi = {__uint_as_float(ur.y << 16), __uint_as_float(ur.y & 0xFFFF0000u)};
;       const f32x2 vv = {v, v};
;       const f32x2 t = Sa * a4.lo + Sb * a4.hi;
;       const f32x2 na = Sa * w4.lo + vv * klo;
;       const f32x2 nb = Sb * w4.hi + vv * khi;
;       float sa = t.x + t.y;
;       float yp = yprev;
;       rowsum16x2(sa, yp);
;       if (s >= 1 && s <= 16) ykeep0 = (jq == s - 1) ? yp : ykeep0;
;       if (s >= 17) ykeep1 = (jq == s - 17) ? yp : ykeep1;
;       const f32x2 sv = {sa, sa};
;       Sa = na + sv * b4.lo;
;       Sb = nb + sv * b4.hi;
;       const f32x2 yy = Sa * rlo + Sb * rhi;
;       yprev = yy.x + yy.y;
;       w4 = w4n; a4 = a4n; b4 = b4n; ur = urn; uk = ukn; v = vn;
;     }
	ds_read_b128 v[228:231], v76 offset:28416
	ds_read_b128 v[240:243], v76 offset:40704
	ds_read_b128 v[224:227], v76 offset:24320
	ds_read_b128 v[232:235], v76 offset:32512
	ds_read_b128 v[52:55], v77 offset:42032
	v_pk_mul_f32 v[56:57], v[4:5], v[12:13]
	v_pk_mul_f32 v[64:65], v[4:5], v[236:237]
	v_pk_fma_f32 v[56:57], v[6:7], v[14:15], v[56:57]
	v_pk_fma_f32 v[64:65], v[6:7], v[238:239], v[64:65]
	v_add_f32_e32 v58, v56, v57
	v_pk_mul_f32 v[60:61], v[48:49], v[24:25] op_sel:[1,0] op_sel_hi:[1,1]
	v_pk_mul_f32 v[62:63], v[48:49], v[26:27] op_sel:[1,0] op_sel_hi:[1,1]
	v_add_f32_dpp v58, v58, v58 quad_perm:[1,0,3,2] row_mask:0xf bank_mask:0xf bound_ctrl:1
	v_pk_fma_f32 v[60:61], v[4:5], v[8:9], v[60:61]
	v_add_f32_e32 v66, v64, v65
	v_add_f32_dpp v58, v58, v58 quad_perm:[2,3,0,1] row_mask:0xf bank_mask:0xf bound_ctrl:1
	v_pk_fma_f32 v[62:63], v[6:7], v[10:11], v[62:63]
	v_add_f32_dpp v70, v70, v70 row_half_mirror row_mask:0xf bank_mask:0x5
	v_add_f32_dpp v58, v58, v58 row_half_mirror row_mask:0xf bank_mask:0xf bound_ctrl:1
	s_nop 0
	v_add_f32_dpp v70, v71, v71 row_half_mirror row_mask:0xf bank_mask:0xa
	ds_read_b128 v[236:239], v76 offset:36608
	v_add_f32_dpp v58, v58, v58 row_mirror row_mask:0xf bank_mask:0xf bound_ctrl:1
	v_pk_fma_f32 v[4:5], v[58:59], v[16:17], v[60:61] op_sel_hi:[0,1,1]
	v_pk_fma_f32 v[6:7], v[58:59], v[18:19], v[62:63] op_sel_hi:[0,1,1]
	s_waitcnt lgkmcnt(7)
	ds_read_b128 v[12:15], v76 offset:28672
	ds_read_b128 v[24:27], v76 offset:40960
	ds_read_b128 v[8:11], v76 offset:24576
	ds_read_b128 v[16:19], v76 offset:32768
	v_pk_mul_f32 v[56:57], v[4:5], v[32:33]
	v_pk_mul_f32 v[64:65], v[4:5], v[20:21]
	v_pk_fma_f32 v[56:57], v[6:7], v[34:35], v[56:57]
	v_pk_fma_f32 v[64:65], v[6:7], v[22:23], v[64:65]
	v_add_f32_e32 v58, v56, v57
	v_pk_mul_f32 v[60:61], v[50:51], v[44:45] op_sel_hi:[0,1]
	v_pk_mul_f32 v[62:63], v[50:51], v[46:47] op_sel_hi:[0,1]
	v_add_f32_dpp v58, v58, v58 quad_perm:[1,0,3,2] row_mask:0xf bank_mask:0xf bound_ctrl:1
	v_pk_fma_f32 v[60:61], v[4:5], v[28:29], v[60:61]
	v_add_f32_e32 v67, v64, v65
	v_add_f32_dpp v58, v58, v58 quad_perm:[2,3,0,1] row_mask:0xf bank_mask:0xf bound_ctrl:1
	v_pk_fma_f32 v[62:63], v[6:7], v[30:31], v[62:63]
	v_add_f32_dpp v72, v66, v66 row_mirror row_mask:0xf bank_mask:0x3
	v_add_f32_dpp v58, v58, v58 row_half_mirror row_mask:0xf bank_mask:0xf bound_ctrl:1
	s_nop 0
	v_add_f32_dpp v72, v67, v67 row_mirror row_mask:0xf bank_mask:0xc
	ds_read_b128 v[20:23], v76 offset:36864
	v_add_f32_dpp v58, v58, v58 row_mirror row_mask:0xf bank_mask:0xf bound_ctrl:1
	v_pk_fma_f32 v[4:5], v[58:59], v[36:37], v[60:61] op_sel_hi:[0,1,1]
	v_pk_fma_f32 v[6:7], v[58:59], v[38:39], v[62:63] op_sel_hi:[0,1,1]
	s_waitcnt lgkmcnt(7)
	ds_read_b128 v[32:35], v76 offset:28928
	ds_read_b128 v[44:47], v76 offset:41216
	ds_read_b128 v[28:31], v76 offset:24832
	ds_read_b128 v[36:39], v76 offset:33024
	v_pk_mul_f32 v[56:57], v[4:5], v[228:229]
	v_pk_mul_f32 v[64:65], v[4:5], v[40:41]
	v_pk_fma_f32 v[56:57], v[6:7], v[230:231], v[56:57]
	v_pk_fma_f32 v[64:65], v[6:7], v[42:43], v[64:65]
	v_add_f32_e32 v58, v56, v57
	v_pk_mul_f32 v[60:61], v[50:51], v[240:241] op_sel:[1,0] op_sel_hi:[1,1]
	v_pk_mul_f32 v[62:63], v[50:51], v[242:243] op_sel:[1,0] op_sel_hi:[1,1]
	v_add_f32_dpp v58, v58, v58 quad_perm:[1,0,3,2] row_mask:0xf bank_mask:0xf bound_ctrl:1
	v_pk_fma_f32 v[60:61], v[4:5], v[224:225], v[60:61]
	v_add_f32_e32 v66, v64, v65
	v_add_f32_dpp v58, v58, v58 quad_perm:[2,3,0,1] row_mask:0xf bank_mask:0xf bound_ctrl:1
	v_pk_fma_f32 v[62:63], v[6:7], v[226:227], v[62:63]
	s_nop 0
	v_add_f32_dpp v58, v58, v58 row_half_mirror row_mask:0xf bank_mask:0xf bound_ctrl:1
	ds_read_b128 v[40:43], v76 offset:37120
	s_nop 0
	v_add_f32_dpp v58, v58, v58 row_mirror row_mask:0xf bank_mask:0xf bound_ctrl:1
	v_pk_fma_f32 v[4:5], v[58:59], v[232:233], v[60:61] op_sel_hi:[0,1,1]
	v_pk_fma_f32 v[6:7], v[58:59], v[234:235], v[62:63] op_sel_hi:[0,1,1]
	s_waitcnt lgkmcnt(6)
	ds_read_b128 v[228:231], v76 offset:29184
	ds_read_b128 v[240:243], v76 offset:41472
	ds_read_b128 v[224:227], v76 offset:25088
	ds_read_b128 v[232:235], v76 offset:33280
	v_pk_mul_f32 v[56:57], v[4:5], v[12:13]
	v_pk_mul_f32 v[64:65], v[4:5], v[236:237]
	v_pk_fma_f32 v[56:57], v[6:7], v[14:15], v[56:57]
	v_pk_fma_f32 v[64:65], v[6:7], v[238:239], v[64:65]
	v_add_f32_e32 v58, v56, v57
	v_pk_mul_f32 v[60:61], v[52:53], v[24:25] op_sel_hi:[0,1]
	v_pk_mul_f32 v[62:63], v[52:53], v[26:27] op_sel_hi:[0,1]
	v_add_f32_dpp v58, v58, v58 quad_perm:[1,0,3,2] row_mask:0xf bank_mask:0xf bound_ctrl:1
	v_pk_fma_f32 v[60:61], v[4:5], v[8:9], v[60:61]
	v_add_f32_e32 v67, v64, v65
	v_add_f32_dpp v58, v58, v58 quad_perm:[2,3,0,1] row_mask:0xf bank_mask:0xf bound_ctrl:1
	v_pk_fma_f32 v[62:63], v[6:7], v[10:11], v[62:63]
	v_add_f32_dpp v73, v66, v66 row_mirror row_mask:0xf bank_mask:0x3
	v_add_f32_dpp v58, v58, v58 row_half_mirror row_mask:0xf bank_mask:0xf bound_ctrl:1
	s_nop 0
	v_add_f32_dpp v73, v67, v67 row_mirror row_mask:0xf bank_mask:0xc
	ds_read_b128 v[236:239], v76 offset:37376
	v_add_f32_dpp v58, v58, v58 row_mirror row_mask:0xf bank_mask:0xf bound_ctrl:1
	v_pk_fma_f32 v[4:5], v[58:59], v[16:17], v[60:61] op_sel_hi:[0,1,1]
	v_pk_fma_f32 v[6:7], v[58:59], v[18:19], v[62:63] op_sel_hi:[0,1,1]
	s_waitcnt lgkmcnt(6)
; DI void scan_task(const Params& p, int l, int isP, int b, int h, int rg, char* smem, const bool dry) {
;     ...
;   auto sstore = [&](int bi) {
;     char* bb = smem + bi * BUFB;
;     *(float4*)(bb + (ds * 64 + dj * 4) * 4) = rd0;
;     *(float4*)(bb + ((16 + ds) * 64 + dj * 4) * 4) = rd1;
;     {
;       CVT8(qa, alo, ahi)
;       float* d = (float*)(bb + 8192) + lst * 64 + lch * 8;
;       *(float4*)d = alo; *(float4*)(d + 4) = ahi;
;     }
;     {
;       CVT8(qb, blo, bhi)
;       float* d = (float*)(bb + 16384) + lst * 64 + lch * 8;
;       *(float4*)d = blo; *(float4*)(d + 4) = bhi;
;     }
;     ...
;     for (int s = 0; s < 32; s++) {
;       f32x4 w4n = w4, a4n = a4, b4n = b4;
;       uint2 urn = ur, ukn = uk;
;       float vn = v;
;       if (s < 31) {
;         w4n = *(const f32x4*)(fw + (s + 1) * 64);
;         a4n = *(const f32x4*)(fa + (s + 1) * 64);
;         b4n = *(const f32x4*)(fb + (s + 1) * 64);
;         urn = *(const uint2*)(pr + (s + 1) * 128);
;         ukn = *(const uint2*)(pk + (s + 1) * 128);
;         vn = vb[(s + 1) * 16];
;       }
;       __builtin_amdgcn_sched_barrier(0);
;       const f32x2 klo = {__uint_as_float(uk.x << 16), __uint_as_float(uk.x & 0xFFFF0000u)};
;       const f32x2 khi = {__uint_as_float(uk.y << 16), __uint_as_float(uk.y & 0xFFFF0000u)};
;       const f32x2 rlo = {__uint_as_float(ur.x << 16), __uint_as_float(ur.x & 0xFFFF0000u)};
;       const f32x2 rhi = {__uint_as_float(ur.y << 16), __uint_as_float(ur.y & 0xFFFF0000u)};
;       const f32x2 vv = {v, v};
;       const f32x2 t = Sa * a4.lo + Sb * a4.hi;
;       const f32x2 na = Sa * w4.lo + vv * klo;
;       const f32x2 nb = Sb * w4.hi + vv * khi;
;       float sa = t.x + t.y;
;       float yp = yprev;
;       rowsum16x2(sa, yp);
;       if (s >= 1 && s <= 16) ykeep0 = (jq == s - 1) ? yp : ykeep0;
;       if (s >= 17) ykeep1 = (jq == s - 17) ? yp : ykeep1;
;       const f32x2 sv = {sa, sa};
;       Sa = na + sv * b4.lo;
;       Sb = nb + sv * b4.hi;
;       const f32x2 yy = Sa * rlo + Sb * rhi;
;       yprev = yy.x + yy.y;
;       w4 = w4n; a4 = a4n; b4 = b4n; ur = urn; uk = ukn; v = vn;
;     }
;     {
;       const float yl = rowsum16(yprev);
;       ykeep1 = (jq == 15) ? yl : ykeep1;
;     }
;     if (!dry) { yo[0] = ykeep0; yo[(size_t)16 * 512] = ykeep1; }
;     if (more) sstore((c + 1) & 1);
;     __syncthreads();
	ds_read_b128 v[12:15], v76 offset:29440
	ds_read_b128 v[24:27], v76 offset:41728
	ds_read_b128 v[8:11], v76 offset:25344
	ds_read_b128 v[16:19], v76 offset:33536
	v_pk_mul_f32 v[56:57], v[4:5], v[32:33]
	v_pk_mul_f32 v[64:65], v[4:5], v[20:21]
	v_pk_fma_f32 v[56:57], v[6:7], v[34:35], v[56:57]
	v_pk_fma_f32 v[64:65], v[6:7], v[22:23], v[64:65]
	v_add_f32_e32 v58, v56, v57
	v_pk_mul_f32 v[60:61], v[52:53], v[44:45] op_sel:[1,0] op_sel_hi:[1,1]
	v_pk_mul_f32 v[62:63], v[52:53], v[46:47] op_sel:[1,0] op_sel_hi:[1,1]
	v_add_f32_dpp v58, v58, v58 quad_perm:[1,0,3,2] row_mask:0xf bank_mask:0xf bound_ctrl:1
	v_pk_fma_f32 v[60:61], v[4:5], v[28:29], v[60:61]
	v_add_f32_e32 v66, v64, v65
	v_add_f32_dpp v58, v58, v58 quad_perm:[2,3,0,1] row_mask:0xf bank_mask:0xf bound_ctrl:1
	v_pk_fma_f32 v[62:63], v[6:7], v[30:31], v[62:63]
	v_add_f32_dpp v72, v72, v72 row_half_mirror row_mask:0xf bank_mask:0x5
	v_add_f32_dpp v58, v58, v58 row_half_mirror row_mask:0xf bank_mask:0xf bound_ctrl:1
	s_nop 0
	v_add_f32_dpp v72, v73, v73 row_half_mirror row_mask:0xf bank_mask:0xa
	ds_read_b128 v[20:23], v76 offset:37632
	v_add_f32_dpp v58, v58, v58 row_mirror row_mask:0xf bank_mask:0xf bound_ctrl:1
	v_pk_fma_f32 v[4:5], v[58:59], v[36:37], v[60:61] op_sel_hi:[0,1,1]
	v_pk_fma_f32 v[6:7], v[58:59], v[38:39], v[62:63] op_sel_hi:[0,1,1]
	s_waitcnt lgkmcnt(6)
	v_pk_mul_f32 v[56:57], v[4:5], v[228:229]
	v_pk_mul_f32 v[64:65], v[4:5], v[40:41]
	v_pk_fma_f32 v[56:57], v[6:7], v[230:231], v[56:57]
	v_pk_fma_f32 v[64:65], v[6:7], v[42:43], v[64:65]
	v_add_f32_e32 v58, v56, v57
	v_pk_mul_f32 v[60:61], v[54:55], v[240:241] op_sel_hi:[0,1]
	v_pk_mul_f32 v[62:63], v[54:55], v[242:243] op_sel_hi:[0,1]
	v_add_f32_dpp v58, v58, v58 quad_perm:[1,0,3,2] row_mask:0xf bank_mask:0xf bound_ctrl:1
	v_pk_fma_f32 v[60:61], v[4:5], v[224:225], v[60:61]
	v_add_f32_e32 v67, v64, v65
	v_add_f32_dpp v58, v58, v58 quad_perm:[2,3,0,1] row_mask:0xf bank_mask:0xf bound_ctrl:1
	v_pk_fma_f32 v[62:63], v[6:7], v[226:227], v[62:63]
	v_add_f32_dpp v74, v66, v66 row_mirror row_mask:0xf bank_mask:0x3
	v_add_f32_dpp v58, v58, v58 row_half_mirror row_mask:0xf bank_mask:0xf bound_ctrl:1
	s_nop 0
	v_add_f32_dpp v74, v67, v67 row_mirror row_mask:0xf bank_mask:0xc
	v_add_f32_dpp v58, v58, v58 row_mirror row_mask:0xf bank_mask:0xf bound_ctrl:1
	v_pk_fma_f32 v[4:5], v[58:59], v[232:233], v[60:61] op_sel_hi:[0,1,1]
	v_pk_fma_f32 v[6:7], v[58:59], v[234:235], v[62:63] op_sel_hi:[0,1,1]
	s_waitcnt lgkmcnt(1)
	v_pk_mul_f32 v[56:57], v[4:5], v[12:13]
	v_pk_mul_f32 v[64:65], v[4:5], v[236:237]
	v_pk_fma_f32 v[56:57], v[6:7], v[14:15], v[56:57]
	v_pk_fma_f32 v[64:65], v[6:7], v[238:239], v[64:65]
	v_add_f32_e32 v58, v56, v57
	v_pk_mul_f32 v[60:61], v[54:55], v[24:25] op_sel:[1,0] op_sel_hi:[1,1]
	v_pk_mul_f32 v[62:63], v[54:55], v[26:27] op_sel:[1,0] op_sel_hi:[1,1]
	v_add_f32_dpp v58, v58, v58 quad_perm:[1,0,3,2] row_mask:0xf bank_mask:0xf bound_ctrl:1
	v_pk_fma_f32 v[60:61], v[4:5], v[8:9], v[60:61]
	v_add_f32_e32 v66, v64, v65
	v_add_f32_dpp v58, v58, v58 quad_perm:[2,3,0,1] row_mask:0xf bank_mask:0xf bound_ctrl:1
	v_pk_fma_f32 v[62:63], v[6:7], v[10:11], v[62:63]
	s_nop 0
	v_add_f32_dpp v58, v58, v58 row_half_mirror row_mask:0xf bank_mask:0xf bound_ctrl:1
	s_nop 1
	v_add_f32_dpp v58, v58, v58 row_mirror row_mask:0xf bank_mask:0xf bound_ctrl:1
	v_pk_fma_f32 v[4:5], v[58:59], v[16:17], v[60:61] op_sel_hi:[0,1,1]
	v_pk_fma_f32 v[6:7], v[58:59], v[18:19], v[62:63] op_sel_hi:[0,1,1]
	s_waitcnt lgkmcnt(0)
	v_pk_mul_f32 v[64:65], v[4:5], v[20:21]
	v_pk_fma_f32 v[64:65], v[6:7], v[22:23], v[64:65]
	v_add_f32_e32 v67, v64, v65
	s_cmp_lg_u32 s22, 0
	s_cbranch_scc0 .Lscan_lastB
	s_waitcnt vmcnt(6)
	ds_write_b128 v78, v[84:87] offset:0
	v_lshlrev_b32_e32 v8, 16, v92
	v_and_b32_e32 v9, 0xffff0000, v92
	v_lshlrev_b32_e32 v10, 16, v93
	v_and_b32_e32 v11, 0xffff0000, v93
	ds_write_b128 v78, v[8:11] offset:4096
	v_lshlrev_b32_e32 v12, 16, v94
	v_and_b32_e32 v13, 0xffff0000, v94
	v_lshlrev_b32_e32 v14, 16, v95
	v_and_b32_e32 v15, 0xffff0000, v95
	ds_write_b128 v78, v[12:15] offset:8192
	v_lshlrev_b32_e32 v16, 16, v88
	v_and_b32_e32 v17, 0xffff0000, v88
	v_lshlrev_b32_e32 v18, 16, v89
	v_and_b32_e32 v19, 0xffff0000, v89
	ds_write_b128 v78, v[16:19] offset:12288
	v_lshlrev_b32_e32 v20, 16, v90
	v_and_b32_e32 v21, 0xffff0000, v90
	v_lshlrev_b32_e32 v22, 16, v91
	v_and_b32_e32 v23, 0xffff0000, v91
	ds_write_b128 v78, v[20:23] offset:16384
	v_lshlrev_b32_e32 v24, 16, v96
	ds_write_b32 v79, v24 offset:20480
	s_waitcnt lgkmcnt(0)
	s_barrier
	ds_read_b128 v[12:15], v76 offset:4096
	ds_read_b128 v[24:27], v76 offset:16384
	ds_read_b128 v[48:51], v77 offset:20480
	ds_read_b128 v[8:11], v76 offset:0
	ds_read_b128 v[16:19], v76 offset:8192
	ds_read_b128 v[20:23], v76 offset:12288
	ds_read_b128 v[32:35], v76 offset:4352
	ds_read_b128 v[44:47], v76 offset:16640
	ds_read_b128 v[28:31], v76 offset:256
	ds_read_b128 v[36:39], v76 offset:8448
	ds_read_b128 v[40:43], v76 offset:12544
	s_branch .Lscan_tailB
